# P3 pooling pre-phase: two items per wait (item loop unrolled by two with separate data registers)
# baseline (speedup 1.0000x reference)
; __global__ void __launch_bounds__(512, 2) hybrid_fwd(Args args) {
;     ...
;             for (int it = tid; it < 256 * 32; it += 512) {
;                 const int t = pu.pm * 256 + (it >> 5), cg8 = pu.pn * 32 + (it & 31), tl = t & 8191, w = 2 << (cg8 >> 4);
;                 const bf16_t* xp = XP + (size_t)t * 512 + cg8 * 8;
;                 float sum[8];
; #pragma unroll
;                 for (int e = 0; e < 8; ++e) sum[e] = 0.f;
;                 u32x4 x0 = (u32x4){0u, 0u, 0u, 0u};
; #pragma unroll
;                 for (int j = 0; j < 16; ++j) {
;                     if (j < w && tl - j >= 0) {
;                         const u32x4 v = *(const u32x4*)(xp - (size_t)j * 512);
;                         if (j == 0) x0 = v;
; #pragma unroll
;                         for (int e = 0; e < 4; ++e) { sum[2 * e] += __builtin_bit_cast(float, v[e] << 16); sum[2 * e + 1] += __builtin_bit_cast(float, v[e] & 0xffff0000u); }
;                     }
.LBB0_368:
	s_and_saveexec_b64 s[52:53], s[6:7]
	s_cbranch_execz .LBB0_359
	v_lshl_or_b32 v0, s64, 5, v27
	v_ashrrev_i32_e32 v2, 4, v0
	v_lshlrev_b32_e32 v0, 3, v0
	v_ashrrev_i32_e32 v1, 31, v0
	v_lshlrev_b32_e64 v28, v2, 2
	v_lshlrev_b64 v[0:1], 1, v[0:1]
	v_cmp_gt_i32_e32 vcc, 2, v28
	v_cmp_gt_i32_e64 s[10:11], 3, v28
	v_cmp_gt_i32_e64 s[12:13], 4, v28
	v_cmp_gt_i32_e64 s[14:15], 5, v28
	v_cmp_gt_i32_e64 s[16:17], 6, v28
	v_cmp_gt_i32_e64 s[18:19], 7, v28
	v_cmp_gt_i32_e64 s[20:21], 8, v28
	v_cmp_gt_i32_e64 s[22:23], 9, v28
	v_cmp_gt_i32_e64 s[24:25], 10, v28
	v_cmp_gt_i32_e64 s[26:27], 11, v28
	v_cmp_gt_i32_e64 s[28:29], 12, v28
	v_cmp_gt_i32_e64 s[30:31], 13, v28
	v_cmp_gt_i32_e64 s[34:35], 14, v28
	v_cmp_gt_i32_e64 s[36:37], 15, v28
	v_cmp_gt_i32_e64 s[38:39], 16, v28
	s_lshl_b32 s66, s65, 8
	v_lshl_add_u64 v[8:9], s[50:51], 0, v[0:1]
	v_cmp_lt_i32_e64 s[8:9], 0, v28
	v_lshl_add_u64 v[10:11], s[42:43], 0, v[0:1]
	s_mov_b64 s[54:55], 0
	s_xor_b64 s[56:57], vcc, -1
	s_xor_b64 s[10:11], s[10:11], -1
	s_xor_b64 s[12:13], s[12:13], -1
	s_xor_b64 s[14:15], s[14:15], -1
	s_xor_b64 s[16:17], s[16:17], -1
	s_xor_b64 s[18:19], s[18:19], -1
	s_xor_b64 s[20:21], s[20:21], -1
	s_xor_b64 s[22:23], s[22:23], -1
	s_xor_b64 s[24:25], s[24:25], -1
	s_xor_b64 s[26:27], s[26:27], -1
	s_xor_b64 s[28:29], s[28:29], -1
	s_xor_b64 s[30:31], s[30:31], -1
	s_xor_b64 s[34:35], s[34:35], -1
	s_xor_b64 s[36:37], s[36:37], -1
	s_xor_b64 s[38:39], s[38:39], -1
	v_mov_b32_e32 v29, v26
	s_mov_b32 s86, 0
.Lp3_loop:
	v_mov_b32_e32 v32, v29
	v_ashrrev_i32_e32 v32, 5, v32
	v_add_u32_e32 v16, s66, v32
	v_ashrrev_i32_e32 v17, 31, v16
	v_lshlrev_b64 v[32:33], 10, v[16:17]
	v_lshl_add_u64 v[22:23], v[8:9], 0, v[32:33]
	v_and_b32_e32 v30, 0x1fff, v16
	v_mov_b32_e32 v0, 0
	v_mov_b32_e32 v1, 0
	v_mov_b32_e32 v2, 0
	v_mov_b32_e32 v3, 0
	v_add_co_u32_e32 v104, vcc, 0xfffff000, v22
	s_nop 1
	v_addc_co_u32_e32 v105, vcc, -1, v23, vcc
	v_add_co_u32_e32 v106, vcc, 0xffffe000, v22
	s_nop 1
	v_addc_co_u32_e32 v107, vcc, -1, v23, vcc
	v_add_co_u32_e32 v108, vcc, 0xffffd000, v22
	s_nop 1
	v_addc_co_u32_e32 v109, vcc, -1, v23, vcc
	s_and_saveexec_b64 s[58:59], s[8:9]
	global_load_dwordx4 v[0:3], v[22:23], off
	s_or_b64 exec, exec, s[58:59]
	v_cmp_ne_u32_e32 vcc, 0, v30
	s_and_b64 s[70:71], s[56:57], vcc
	s_and_saveexec_b64 s[58:59], s[70:71]
	global_load_dwordx4 v[44:47], v[22:23], off offset:-1024
	s_or_b64 exec, exec, s[58:59]
	v_cmp_lt_u32_e32 vcc, 1, v30
	s_and_b64 s[70:71], s[10:11], vcc
	s_and_saveexec_b64 s[58:59], s[70:71]
	global_load_dwordx4 v[48:51], v[22:23], off offset:-2048
	s_or_b64 exec, exec, s[58:59]
	v_cmp_lt_u32_e32 vcc, 2, v30
	s_and_b64 s[70:71], s[12:13], vcc
	s_and_saveexec_b64 s[58:59], s[70:71]
	global_load_dwordx4 v[52:55], v[22:23], off offset:-3072
	s_or_b64 exec, exec, s[58:59]
	v_cmp_lt_u32_e32 vcc, 3, v30
	s_and_b64 s[70:71], s[14:15], vcc
	s_and_saveexec_b64 s[58:59], s[70:71]
	global_load_dwordx4 v[56:59], v[104:105], off
	s_or_b64 exec, exec, s[58:59]
	v_cmp_lt_u32_e32 vcc, 4, v30
	s_and_b64 s[70:71], s[16:17], vcc
	s_and_saveexec_b64 s[58:59], s[70:71]
	global_load_dwordx4 v[60:63], v[104:105], off offset:-1024
	s_or_b64 exec, exec, s[58:59]
	v_cmp_lt_u32_e32 vcc, 5, v30
	s_and_b64 s[70:71], s[18:19], vcc
	s_and_saveexec_b64 s[58:59], s[70:71]
	global_load_dwordx4 v[64:67], v[104:105], off offset:-2048
	s_or_b64 exec, exec, s[58:59]
	v_cmp_lt_u32_e32 vcc, 6, v30
	s_and_b64 s[70:71], s[20:21], vcc
	s_and_saveexec_b64 s[58:59], s[70:71]
	global_load_dwordx4 v[68:71], v[104:105], off offset:-3072
	s_or_b64 exec, exec, s[58:59]
	v_cmp_lt_u32_e32 vcc, 7, v30
	s_and_b64 s[70:71], s[22:23], vcc
	s_and_saveexec_b64 s[58:59], s[70:71]
	global_load_dwordx4 v[72:75], v[106:107], off
	s_or_b64 exec, exec, s[58:59]
	v_cmp_lt_u32_e32 vcc, 8, v30
	s_and_b64 s[70:71], s[24:25], vcc
	s_and_saveexec_b64 s[58:59], s[70:71]
	global_load_dwordx4 v[76:79], v[106:107], off offset:-1024
	s_or_b64 exec, exec, s[58:59]
	v_cmp_lt_u32_e32 vcc, 9, v30
	s_and_b64 s[70:71], s[26:27], vcc
	s_and_saveexec_b64 s[58:59], s[70:71]
	global_load_dwordx4 v[80:83], v[106:107], off offset:-2048
	s_or_b64 exec, exec, s[58:59]
	v_cmp_lt_u32_e32 vcc, 10, v30
	s_and_b64 s[70:71], s[28:29], vcc
	s_and_saveexec_b64 s[58:59], s[70:71]
	global_load_dwordx4 v[84:87], v[106:107], off offset:-3072
	s_or_b64 exec, exec, s[58:59]
	v_cmp_lt_u32_e32 vcc, 11, v30
	s_and_b64 s[70:71], s[30:31], vcc
	s_and_saveexec_b64 s[58:59], s[70:71]
	global_load_dwordx4 v[88:91], v[108:109], off
	s_or_b64 exec, exec, s[58:59]
	v_cmp_lt_u32_e32 vcc, 12, v30
	s_and_b64 s[70:71], s[34:35], vcc
	s_and_saveexec_b64 s[58:59], s[70:71]
	global_load_dwordx4 v[92:95], v[108:109], off offset:-1024
	s_or_b64 exec, exec, s[58:59]
	v_cmp_lt_u32_e32 vcc, 13, v30
	s_and_b64 s[70:71], s[36:37], vcc
	s_and_saveexec_b64 s[58:59], s[70:71]
	global_load_dwordx4 v[96:99], v[108:109], off offset:-2048
	s_or_b64 exec, exec, s[58:59]
	v_cmp_lt_u32_e32 vcc, 14, v30
	s_and_b64 s[70:71], s[38:39], vcc
	s_and_saveexec_b64 s[58:59], s[70:71]
	global_load_dwordx4 v[100:103], v[108:109], off offset:-3072
	s_or_b64 exec, exec, s[58:59]
	v_add_u32_e32 v32, 0x200, v29
	v_ashrrev_i32_e32 v32, 5, v32
	v_add_u32_e32 v174, s66, v32
	v_ashrrev_i32_e32 v175, 31, v174
	v_lshlrev_b64 v[32:33], 10, v[174:175]
	v_lshl_add_u64 v[22:23], v[8:9], 0, v[32:33]
	v_and_b32_e32 v176, 0x1fff, v174
	v_mov_b32_e32 v110, 0
	v_mov_b32_e32 v111, 0
	v_mov_b32_e32 v112, 0
	v_mov_b32_e32 v113, 0
	v_add_co_u32_e32 v104, vcc, 0xfffff000, v22
	s_nop 1
	v_addc_co_u32_e32 v105, vcc, -1, v23, vcc
	v_add_co_u32_e32 v106, vcc, 0xffffe000, v22
	s_nop 1
	v_addc_co_u32_e32 v107, vcc, -1, v23, vcc
; __global__ void __launch_bounds__(512, 2) hybrid_fwd(Args args) {
;     ...
;                 for (int j = 0; j < 16; ++j) {
;                     if (j < w && tl - j >= 0) {
;                         const u32x4 v = *(const u32x4*)(xp - (size_t)j * 512);
;                         if (j == 0) x0 = v;
; #pragma unroll
;                         for (int e = 0; e < 4; ++e) { sum[2 * e] += __builtin_bit_cast(float, v[e] << 16); sum[2 * e + 1] += __builtin_bit_cast(float, v[e] & 0xffff0000u); }
	v_add_co_u32_e32 v108, vcc, 0xffffd000, v22
	s_nop 1
	v_addc_co_u32_e32 v109, vcc, -1, v23, vcc
	s_and_saveexec_b64 s[58:59], s[8:9]
	global_load_dwordx4 v[110:113], v[22:23], off
	s_or_b64 exec, exec, s[58:59]
	v_cmp_ne_u32_e32 vcc, 0, v176
	s_and_b64 s[70:71], s[56:57], vcc
	s_and_saveexec_b64 s[58:59], s[70:71]
	global_load_dwordx4 v[114:117], v[22:23], off offset:-1024
	s_or_b64 exec, exec, s[58:59]
	v_cmp_lt_u32_e32 vcc, 1, v176
	s_and_b64 s[70:71], s[10:11], vcc
	s_and_saveexec_b64 s[58:59], s[70:71]
	global_load_dwordx4 v[118:121], v[22:23], off offset:-2048
	s_or_b64 exec, exec, s[58:59]
	v_cmp_lt_u32_e32 vcc, 2, v176
	s_and_b64 s[70:71], s[12:13], vcc
	s_and_saveexec_b64 s[58:59], s[70:71]
	global_load_dwordx4 v[122:125], v[22:23], off offset:-3072
	s_or_b64 exec, exec, s[58:59]
	v_cmp_lt_u32_e32 vcc, 3, v176
	s_and_b64 s[70:71], s[14:15], vcc
	s_and_saveexec_b64 s[58:59], s[70:71]
	global_load_dwordx4 v[126:129], v[104:105], off
	s_or_b64 exec, exec, s[58:59]
	v_cmp_lt_u32_e32 vcc, 4, v176
	s_and_b64 s[70:71], s[16:17], vcc
	s_and_saveexec_b64 s[58:59], s[70:71]
	global_load_dwordx4 v[130:133], v[104:105], off offset:-1024
	s_or_b64 exec, exec, s[58:59]
	v_cmp_lt_u32_e32 vcc, 5, v176
	s_and_b64 s[70:71], s[18:19], vcc
	s_and_saveexec_b64 s[58:59], s[70:71]
	global_load_dwordx4 v[134:137], v[104:105], off offset:-2048
	s_or_b64 exec, exec, s[58:59]
	v_cmp_lt_u32_e32 vcc, 6, v176
	s_and_b64 s[70:71], s[20:21], vcc
	s_and_saveexec_b64 s[58:59], s[70:71]
	global_load_dwordx4 v[138:141], v[104:105], off offset:-3072
	s_or_b64 exec, exec, s[58:59]
	v_cmp_lt_u32_e32 vcc, 7, v176
	s_and_b64 s[70:71], s[22:23], vcc
	s_and_saveexec_b64 s[58:59], s[70:71]
	global_load_dwordx4 v[142:145], v[106:107], off
	s_or_b64 exec, exec, s[58:59]
	v_cmp_lt_u32_e32 vcc, 8, v176
	s_and_b64 s[70:71], s[24:25], vcc
	s_and_saveexec_b64 s[58:59], s[70:71]
	global_load_dwordx4 v[146:149], v[106:107], off offset:-1024
	s_or_b64 exec, exec, s[58:59]
	v_cmp_lt_u32_e32 vcc, 9, v176
	s_and_b64 s[70:71], s[26:27], vcc
	s_and_saveexec_b64 s[58:59], s[70:71]
	global_load_dwordx4 v[150:153], v[106:107], off offset:-2048
	s_or_b64 exec, exec, s[58:59]
	v_cmp_lt_u32_e32 vcc, 10, v176
	s_and_b64 s[70:71], s[28:29], vcc
	s_and_saveexec_b64 s[58:59], s[70:71]
	global_load_dwordx4 v[154:157], v[106:107], off offset:-3072
	s_or_b64 exec, exec, s[58:59]
	v_cmp_lt_u32_e32 vcc, 11, v176
	s_and_b64 s[70:71], s[30:31], vcc
	s_and_saveexec_b64 s[58:59], s[70:71]
	global_load_dwordx4 v[158:161], v[108:109], off
	s_or_b64 exec, exec, s[58:59]
	v_cmp_lt_u32_e32 vcc, 12, v176
	s_and_b64 s[70:71], s[34:35], vcc
	s_and_saveexec_b64 s[58:59], s[70:71]
	global_load_dwordx4 v[162:165], v[108:109], off offset:-1024
	s_or_b64 exec, exec, s[58:59]
	v_cmp_lt_u32_e32 vcc, 13, v176
	s_and_b64 s[70:71], s[36:37], vcc
	s_and_saveexec_b64 s[58:59], s[70:71]
	global_load_dwordx4 v[166:169], v[108:109], off offset:-2048
	s_or_b64 exec, exec, s[58:59]
	v_cmp_lt_u32_e32 vcc, 14, v176
	s_and_b64 s[70:71], s[38:39], vcc
	s_and_saveexec_b64 s[58:59], s[70:71]
	global_load_dwordx4 v[170:173], v[108:109], off offset:-3072
	s_or_b64 exec, exec, s[58:59]
	s_waitcnt vmcnt(0)
	v_mov_b32_e32 v24, 0
	v_mov_b32_e32 v25, 0
	v_mov_b32_e32 v18, 0
	v_mov_b32_e32 v19, 0
	v_mov_b32_e32 v14, 0
	v_mov_b32_e32 v15, 0
	v_mov_b32_e32 v12, 0
	v_mov_b32_e32 v13, 0
	v_mov_b32_e32 v20, 0
	v_mov_b32_e32 v21, 0
	s_and_saveexec_b64 s[58:59], s[8:9]
	v_lshlrev_b32_e32 v24, 16, v3
	v_and_b32_e32 v25, 0xffff0000, v3
	v_lshlrev_b32_e32 v12, 16, v0
	v_and_b32_e32 v13, 0xffff0000, v0
	v_lshlrev_b32_e32 v14, 16, v1
	v_and_b32_e32 v15, 0xffff0000, v1
	v_lshlrev_b32_e32 v20, 16, v2
	v_and_b32_e32 v21, 0xffff0000, v2
	v_pk_add_f32 v[24:25], v[24:25], 0 op_sel_hi:[1,0]
	v_pk_add_f32 v[18:19], v[12:13], 0 op_sel_hi:[1,0]
	v_pk_add_f32 v[14:15], v[14:15], 0 op_sel_hi:[1,0]
	v_pk_add_f32 v[12:13], v[20:21], 0 op_sel_hi:[1,0]
	v_mov_b32_e32 v20, v24
	v_mov_b32_e32 v21, v25
	s_or_b64 exec, exec, s[58:59]
	v_cmp_ne_u32_e32 vcc, 0, v30
	s_and_b64 s[70:71], s[56:57], vcc
	s_and_saveexec_b64 s[58:59], s[70:71]
	v_lshlrev_b32_e32 v32, 16, v44
	v_and_b32_e32 v33, 0xffff0000, v44
	v_lshlrev_b32_e32 v34, 16, v45
	v_and_b32_e32 v35, 0xffff0000, v45
	v_lshlrev_b32_e32 v36, 16, v46
	v_and_b32_e32 v37, 0xffff0000, v46
	v_lshlrev_b32_e32 v38, 16, v47
	v_and_b32_e32 v39, 0xffff0000, v47
	v_pk_add_f32 v[18:19], v[18:19], v[32:33]
	v_pk_add_f32 v[14:15], v[14:15], v[34:35]
	v_pk_add_f32 v[12:13], v[12:13], v[36:37]
	v_pk_add_f32 v[20:21], v[20:21], v[38:39]
	s_or_b64 exec, exec, s[58:59]
	v_cmp_lt_u32_e32 vcc, 1, v30
	s_and_b64 s[70:71], s[10:11], vcc
	s_and_saveexec_b64 s[58:59], s[70:71]
	v_lshlrev_b32_e32 v32, 16, v48
	v_and_b32_e32 v33, 0xffff0000, v48
	v_lshlrev_b32_e32 v34, 16, v49
	v_and_b32_e32 v35, 0xffff0000, v49
	v_lshlrev_b32_e32 v36, 16, v50
	v_and_b32_e32 v37, 0xffff0000, v50
	v_lshlrev_b32_e32 v38, 16, v51
	v_and_b32_e32 v39, 0xffff0000, v51
	v_pk_add_f32 v[18:19], v[18:19], v[32:33]
	v_pk_add_f32 v[14:15], v[14:15], v[34:35]
	v_pk_add_f32 v[12:13], v[12:13], v[36:37]
	v_pk_add_f32 v[20:21], v[20:21], v[38:39]
	s_or_b64 exec, exec, s[58:59]
	v_cmp_lt_u32_e32 vcc, 2, v30
	s_and_b64 s[70:71], s[12:13], vcc
	s_and_saveexec_b64 s[58:59], s[70:71]
	v_lshlrev_b32_e32 v32, 16, v52
	v_and_b32_e32 v33, 0xffff0000, v52
	v_lshlrev_b32_e32 v34, 16, v53
	v_and_b32_e32 v35, 0xffff0000, v53
	v_lshlrev_b32_e32 v36, 16, v54
	v_and_b32_e32 v37, 0xffff0000, v54
	v_lshlrev_b32_e32 v38, 16, v55
	v_and_b32_e32 v39, 0xffff0000, v55
	v_pk_add_f32 v[18:19], v[18:19], v[32:33]
	v_pk_add_f32 v[14:15], v[14:15], v[34:35]
	v_pk_add_f32 v[12:13], v[12:13], v[36:37]
; __global__ void __launch_bounds__(512, 2) hybrid_fwd(Args args) {
;     ...
;                 for (int j = 0; j < 16; ++j) {
;                     if (j < w && tl - j >= 0) {
;                         const u32x4 v = *(const u32x4*)(xp - (size_t)j * 512);
;                         if (j == 0) x0 = v;
; #pragma unroll
;                         for (int e = 0; e < 4; ++e) { sum[2 * e] += __builtin_bit_cast(float, v[e] << 16); sum[2 * e + 1] += __builtin_bit_cast(float, v[e] & 0xffff0000u); }
	v_pk_add_f32 v[20:21], v[20:21], v[38:39]
	s_or_b64 exec, exec, s[58:59]
	v_cmp_lt_u32_e32 vcc, 3, v30
	s_and_b64 s[70:71], s[14:15], vcc
	s_and_saveexec_b64 s[58:59], s[70:71]
	v_lshlrev_b32_e32 v32, 16, v56
	v_and_b32_e32 v33, 0xffff0000, v56
	v_lshlrev_b32_e32 v34, 16, v57
	v_and_b32_e32 v35, 0xffff0000, v57
	v_lshlrev_b32_e32 v36, 16, v58
	v_and_b32_e32 v37, 0xffff0000, v58
	v_lshlrev_b32_e32 v38, 16, v59
	v_and_b32_e32 v39, 0xffff0000, v59
	v_pk_add_f32 v[18:19], v[18:19], v[32:33]
	v_pk_add_f32 v[14:15], v[14:15], v[34:35]
	v_pk_add_f32 v[12:13], v[12:13], v[36:37]
	v_pk_add_f32 v[20:21], v[20:21], v[38:39]
	s_or_b64 exec, exec, s[58:59]
	v_cmp_lt_u32_e32 vcc, 4, v30
	s_and_b64 s[70:71], s[16:17], vcc
	s_and_saveexec_b64 s[58:59], s[70:71]
	v_lshlrev_b32_e32 v32, 16, v60
	v_and_b32_e32 v33, 0xffff0000, v60
	v_lshlrev_b32_e32 v34, 16, v61
	v_and_b32_e32 v35, 0xffff0000, v61
	v_lshlrev_b32_e32 v36, 16, v62
	v_and_b32_e32 v37, 0xffff0000, v62
	v_lshlrev_b32_e32 v38, 16, v63
	v_and_b32_e32 v39, 0xffff0000, v63
	v_pk_add_f32 v[18:19], v[18:19], v[32:33]
	v_pk_add_f32 v[14:15], v[14:15], v[34:35]
	v_pk_add_f32 v[12:13], v[12:13], v[36:37]
	v_pk_add_f32 v[20:21], v[20:21], v[38:39]
	s_or_b64 exec, exec, s[58:59]
	v_cmp_lt_u32_e32 vcc, 5, v30
	s_and_b64 s[70:71], s[18:19], vcc
	s_and_saveexec_b64 s[58:59], s[70:71]
	v_lshlrev_b32_e32 v32, 16, v64
	v_and_b32_e32 v33, 0xffff0000, v64
	v_lshlrev_b32_e32 v34, 16, v65
	v_and_b32_e32 v35, 0xffff0000, v65
	v_lshlrev_b32_e32 v36, 16, v66
	v_and_b32_e32 v37, 0xffff0000, v66
	v_lshlrev_b32_e32 v38, 16, v67
	v_and_b32_e32 v39, 0xffff0000, v67
	v_pk_add_f32 v[18:19], v[18:19], v[32:33]
	v_pk_add_f32 v[14:15], v[14:15], v[34:35]
	v_pk_add_f32 v[12:13], v[12:13], v[36:37]
	v_pk_add_f32 v[20:21], v[20:21], v[38:39]
	s_or_b64 exec, exec, s[58:59]
	v_cmp_lt_u32_e32 vcc, 6, v30
	s_and_b64 s[70:71], s[20:21], vcc
	s_and_saveexec_b64 s[58:59], s[70:71]
	v_lshlrev_b32_e32 v32, 16, v68
	v_and_b32_e32 v33, 0xffff0000, v68
	v_lshlrev_b32_e32 v34, 16, v69
	v_and_b32_e32 v35, 0xffff0000, v69
	v_lshlrev_b32_e32 v36, 16, v70
	v_and_b32_e32 v37, 0xffff0000, v70
	v_lshlrev_b32_e32 v38, 16, v71
	v_and_b32_e32 v39, 0xffff0000, v71
	v_pk_add_f32 v[18:19], v[18:19], v[32:33]
	v_pk_add_f32 v[14:15], v[14:15], v[34:35]
	v_pk_add_f32 v[12:13], v[12:13], v[36:37]
	v_pk_add_f32 v[20:21], v[20:21], v[38:39]
	s_or_b64 exec, exec, s[58:59]
	v_cmp_lt_u32_e32 vcc, 7, v30
	s_and_b64 s[70:71], s[22:23], vcc
	s_and_saveexec_b64 s[58:59], s[70:71]
	v_lshlrev_b32_e32 v32, 16, v72
	v_and_b32_e32 v33, 0xffff0000, v72
	v_lshlrev_b32_e32 v34, 16, v73
	v_and_b32_e32 v35, 0xffff0000, v73
	v_lshlrev_b32_e32 v36, 16, v74
	v_and_b32_e32 v37, 0xffff0000, v74
	v_lshlrev_b32_e32 v38, 16, v75
	v_and_b32_e32 v39, 0xffff0000, v75
	v_pk_add_f32 v[18:19], v[18:19], v[32:33]
	v_pk_add_f32 v[14:15], v[14:15], v[34:35]
	v_pk_add_f32 v[12:13], v[12:13], v[36:37]
	v_pk_add_f32 v[20:21], v[20:21], v[38:39]
	s_or_b64 exec, exec, s[58:59]
	v_cmp_lt_u32_e32 vcc, 8, v30
	s_and_b64 s[70:71], s[24:25], vcc
	s_and_saveexec_b64 s[58:59], s[70:71]
	v_lshlrev_b32_e32 v32, 16, v76
	v_and_b32_e32 v33, 0xffff0000, v76
	v_lshlrev_b32_e32 v34, 16, v77
	v_and_b32_e32 v35, 0xffff0000, v77
	v_lshlrev_b32_e32 v36, 16, v78
	v_and_b32_e32 v37, 0xffff0000, v78
	v_lshlrev_b32_e32 v38, 16, v79
	v_and_b32_e32 v39, 0xffff0000, v79
	v_pk_add_f32 v[18:19], v[18:19], v[32:33]
	v_pk_add_f32 v[14:15], v[14:15], v[34:35]
	v_pk_add_f32 v[12:13], v[12:13], v[36:37]
	v_pk_add_f32 v[20:21], v[20:21], v[38:39]
	s_or_b64 exec, exec, s[58:59]
	v_cmp_lt_u32_e32 vcc, 9, v30
	s_and_b64 s[70:71], s[26:27], vcc
	s_and_saveexec_b64 s[58:59], s[70:71]
	v_lshlrev_b32_e32 v32, 16, v80
	v_and_b32_e32 v33, 0xffff0000, v80
	v_lshlrev_b32_e32 v34, 16, v81
	v_and_b32_e32 v35, 0xffff0000, v81
	v_lshlrev_b32_e32 v36, 16, v82
	v_and_b32_e32 v37, 0xffff0000, v82
	v_lshlrev_b32_e32 v38, 16, v83
	v_and_b32_e32 v39, 0xffff0000, v83
	v_pk_add_f32 v[18:19], v[18:19], v[32:33]
	v_pk_add_f32 v[14:15], v[14:15], v[34:35]
	v_pk_add_f32 v[12:13], v[12:13], v[36:37]
	v_pk_add_f32 v[20:21], v[20:21], v[38:39]
	s_or_b64 exec, exec, s[58:59]
	v_cmp_lt_u32_e32 vcc, 10, v30
	s_and_b64 s[70:71], s[28:29], vcc
	s_and_saveexec_b64 s[58:59], s[70:71]
	v_lshlrev_b32_e32 v32, 16, v84
	v_and_b32_e32 v33, 0xffff0000, v84
	v_lshlrev_b32_e32 v34, 16, v85
	v_and_b32_e32 v35, 0xffff0000, v85
	v_lshlrev_b32_e32 v36, 16, v86
	v_and_b32_e32 v37, 0xffff0000, v86
	v_lshlrev_b32_e32 v38, 16, v87
	v_and_b32_e32 v39, 0xffff0000, v87
	v_pk_add_f32 v[18:19], v[18:19], v[32:33]
	v_pk_add_f32 v[14:15], v[14:15], v[34:35]
	v_pk_add_f32 v[12:13], v[12:13], v[36:37]
	v_pk_add_f32 v[20:21], v[20:21], v[38:39]
	s_or_b64 exec, exec, s[58:59]
	v_cmp_lt_u32_e32 vcc, 11, v30
	s_and_b64 s[70:71], s[30:31], vcc
	s_and_saveexec_b64 s[58:59], s[70:71]
	v_lshlrev_b32_e32 v32, 16, v88
	v_and_b32_e32 v33, 0xffff0000, v88
	v_lshlrev_b32_e32 v34, 16, v89
	v_and_b32_e32 v35, 0xffff0000, v89
	v_lshlrev_b32_e32 v36, 16, v90
	v_and_b32_e32 v37, 0xffff0000, v90
	v_lshlrev_b32_e32 v38, 16, v91
	v_and_b32_e32 v39, 0xffff0000, v91
	v_pk_add_f32 v[18:19], v[18:19], v[32:33]
	v_pk_add_f32 v[14:15], v[14:15], v[34:35]
	v_pk_add_f32 v[12:13], v[12:13], v[36:37]
	v_pk_add_f32 v[20:21], v[20:21], v[38:39]
	s_or_b64 exec, exec, s[58:59]
	v_cmp_lt_u32_e32 vcc, 12, v30
	s_and_b64 s[70:71], s[34:35], vcc
	s_and_saveexec_b64 s[58:59], s[70:71]
	v_lshlrev_b32_e32 v32, 16, v92
	v_and_b32_e32 v33, 0xffff0000, v92
	v_lshlrev_b32_e32 v34, 16, v93
	v_and_b32_e32 v35, 0xffff0000, v93
	v_lshlrev_b32_e32 v36, 16, v94
	v_and_b32_e32 v37, 0xffff0000, v94
	v_lshlrev_b32_e32 v38, 16, v95
; __device__ __forceinline__ unsigned cvt_pk_bf16(float lo, float hi) { f32x2_t v = {lo, hi}; bf16x2_t b = __builtin_convertvector(v, bf16x2_t); return __builtin_bit_cast(unsigned, b); }
; __global__ void __launch_bounds__(512, 2) hybrid_fwd(Args args) {
;     ...
;                 for (int j = 0; j < 16; ++j) {
;                     if (j < w && tl - j >= 0) {
;                         const u32x4 v = *(const u32x4*)(xp - (size_t)j * 512);
;                         if (j == 0) x0 = v;
; #pragma unroll
;                         for (int e = 0; e < 4; ++e) { sum[2 * e] += __builtin_bit_cast(float, v[e] << 16); sum[2 * e + 1] += __builtin_bit_cast(float, v[e] & 0xffff0000u); }
;                     }
;                 }
;                 const float inv = 1.0f / (float)(tl + 1 < w ? tl + 1 : w);
;                 float p[8];
; #pragma unroll
;                 for (int e = 0; e < 4; ++e) { p[2 * e] = sum[2 * e] * inv - __builtin_bit_cast(float, x0[e] << 16); p[2 * e + 1] = sum[2 * e + 1] * inv - __builtin_bit_cast(float, x0[e] & 0xffff0000u); }
;                 u32x4 o; o.x = cvt_pk_bf16(p[0], p[1]); o.y = cvt_pk_bf16(p[2], p[3]); o.z = cvt_pk_bf16(p[4], p[5]); o.w = cvt_pk_bf16(p[6], p[7]);
;                 *(u32x4*)(POOLED + (size_t)t * 512 + cg8 * 8) = o;
	v_and_b32_e32 v39, 0xffff0000, v95
	v_pk_add_f32 v[18:19], v[18:19], v[32:33]
	v_pk_add_f32 v[14:15], v[14:15], v[34:35]
	v_pk_add_f32 v[12:13], v[12:13], v[36:37]
	v_pk_add_f32 v[20:21], v[20:21], v[38:39]
	s_or_b64 exec, exec, s[58:59]
	v_cmp_lt_u32_e32 vcc, 13, v30
	s_and_b64 s[70:71], s[36:37], vcc
	s_and_saveexec_b64 s[58:59], s[70:71]
	v_lshlrev_b32_e32 v32, 16, v96
	v_and_b32_e32 v33, 0xffff0000, v96
	v_lshlrev_b32_e32 v34, 16, v97
	v_and_b32_e32 v35, 0xffff0000, v97
	v_lshlrev_b32_e32 v36, 16, v98
	v_and_b32_e32 v37, 0xffff0000, v98
	v_lshlrev_b32_e32 v38, 16, v99
	v_and_b32_e32 v39, 0xffff0000, v99
	v_pk_add_f32 v[18:19], v[18:19], v[32:33]
	v_pk_add_f32 v[14:15], v[14:15], v[34:35]
	v_pk_add_f32 v[12:13], v[12:13], v[36:37]
	v_pk_add_f32 v[20:21], v[20:21], v[38:39]
	s_or_b64 exec, exec, s[58:59]
	v_cmp_lt_u32_e32 vcc, 14, v30
	s_and_b64 s[70:71], s[38:39], vcc
	s_and_saveexec_b64 s[58:59], s[70:71]
	v_lshlrev_b32_e32 v32, 16, v100
	v_and_b32_e32 v33, 0xffff0000, v100
	v_lshlrev_b32_e32 v34, 16, v101
	v_and_b32_e32 v35, 0xffff0000, v101
	v_lshlrev_b32_e32 v36, 16, v102
	v_and_b32_e32 v37, 0xffff0000, v102
	v_lshlrev_b32_e32 v38, 16, v103
	v_and_b32_e32 v39, 0xffff0000, v103
	v_pk_add_f32 v[18:19], v[18:19], v[32:33]
	v_pk_add_f32 v[14:15], v[14:15], v[34:35]
	v_pk_add_f32 v[12:13], v[12:13], v[36:37]
	v_pk_add_f32 v[20:21], v[20:21], v[38:39]
	s_or_b64 exec, exec, s[58:59]
	v_add_u32_e32 v22, 1, v30
	v_min_i32_e32 v22, v22, v28
	v_cvt_f32_i32_e32 v23, v22
	v_lshlrev_b32_e32 v22, 16, v0
	v_lshlrev_b64 v[16:17], 9, v[16:17]
	v_div_scale_f32 v24, s[58:59], v23, v23, 1.0
	v_rcp_f32_e32 v25, v24
	v_div_scale_f32 v30, vcc, 1.0, v23, 1.0
	v_fma_f32 v31, -v24, v25, 1.0
	v_fmac_f32_e32 v25, v31, v25
	v_mul_f32_e32 v31, v30, v25
	v_fma_f32 v32, -v24, v31, v30
	v_fmac_f32_e32 v31, v32, v25
	v_fma_f32 v24, -v24, v31, v30
	v_div_fmas_f32 v24, v24, v25, v31
	v_div_fixup_f32 v24, v24, v23, 1.0
	v_and_b32_e32 v23, 0xffff0000, v0
	v_lshlrev_b32_e32 v0, 16, v1
	v_and_b32_e32 v1, 0xffff0000, v1
	v_pk_fma_f32 v[14:15], v[24:25], v[14:15], v[0:1] op_sel_hi:[0,1,1] neg_lo:[0,0,1] neg_hi:[0,0,1]
	v_lshlrev_b32_e32 v0, 16, v2
	v_and_b32_e32 v1, 0xffff0000, v2
	v_pk_fma_f32 v[12:13], v[24:25], v[12:13], v[0:1] op_sel_hi:[0,1,1] neg_lo:[0,0,1] neg_hi:[0,0,1]
	v_lshlrev_b32_e32 v0, 16, v3
	v_and_b32_e32 v1, 0xffff0000, v3
	v_pk_fma_f32 v[18:19], v[24:25], v[18:19], v[22:23] op_sel_hi:[0,1,1] neg_lo:[0,0,1] neg_hi:[0,0,1]
	v_pk_fma_f32 v[20:21], v[24:25], v[20:21], v[0:1] op_sel_hi:[0,1,1] neg_lo:[0,0,1] neg_hi:[0,0,1]
	v_cvt_pk_bf16_f32 v0, v18, v19
	v_cvt_pk_bf16_f32 v1, v14, v15
	v_cvt_pk_bf16_f32 v2, v12, v13
	v_cvt_pk_bf16_f32 v3, v20, v21
	v_lshl_add_u64 v[12:13], v[16:17], 1, v[10:11]
	global_store_dwordx4 v[12:13], v[0:3], off
	v_mov_b32_e32 v24, 0
	v_mov_b32_e32 v25, 0
	v_mov_b32_e32 v18, 0
	v_mov_b32_e32 v19, 0
	v_mov_b32_e32 v14, 0
	v_mov_b32_e32 v15, 0
	v_mov_b32_e32 v12, 0
	v_mov_b32_e32 v13, 0
	v_mov_b32_e32 v20, 0
	v_mov_b32_e32 v21, 0
	s_and_saveexec_b64 s[58:59], s[8:9]
	v_lshlrev_b32_e32 v24, 16, v113
	v_and_b32_e32 v25, 0xffff0000, v113
	v_lshlrev_b32_e32 v12, 16, v110
	v_and_b32_e32 v13, 0xffff0000, v110
	v_lshlrev_b32_e32 v14, 16, v111
	v_and_b32_e32 v15, 0xffff0000, v111
	v_lshlrev_b32_e32 v20, 16, v112
	v_and_b32_e32 v21, 0xffff0000, v112
	v_pk_add_f32 v[24:25], v[24:25], 0 op_sel_hi:[1,0]
	v_pk_add_f32 v[18:19], v[12:13], 0 op_sel_hi:[1,0]
	v_pk_add_f32 v[14:15], v[14:15], 0 op_sel_hi:[1,0]
	v_pk_add_f32 v[12:13], v[20:21], 0 op_sel_hi:[1,0]
	v_mov_b32_e32 v20, v24
	v_mov_b32_e32 v21, v25
	s_or_b64 exec, exec, s[58:59]
	v_cmp_ne_u32_e32 vcc, 0, v176
	s_and_b64 s[70:71], s[56:57], vcc
	s_and_saveexec_b64 s[58:59], s[70:71]
	v_lshlrev_b32_e32 v32, 16, v114
	v_and_b32_e32 v33, 0xffff0000, v114
	v_lshlrev_b32_e32 v34, 16, v115
	v_and_b32_e32 v35, 0xffff0000, v115
	v_lshlrev_b32_e32 v36, 16, v116
	v_and_b32_e32 v37, 0xffff0000, v116
	v_lshlrev_b32_e32 v38, 16, v117
	v_and_b32_e32 v39, 0xffff0000, v117
	v_pk_add_f32 v[18:19], v[18:19], v[32:33]
	v_pk_add_f32 v[14:15], v[14:15], v[34:35]
	v_pk_add_f32 v[12:13], v[12:13], v[36:37]
	v_pk_add_f32 v[20:21], v[20:21], v[38:39]
	s_or_b64 exec, exec, s[58:59]
	v_cmp_lt_u32_e32 vcc, 1, v176
	s_and_b64 s[70:71], s[10:11], vcc
	s_and_saveexec_b64 s[58:59], s[70:71]
	v_lshlrev_b32_e32 v32, 16, v118
	v_and_b32_e32 v33, 0xffff0000, v118
	v_lshlrev_b32_e32 v34, 16, v119
	v_and_b32_e32 v35, 0xffff0000, v119
	v_lshlrev_b32_e32 v36, 16, v120
	v_and_b32_e32 v37, 0xffff0000, v120
	v_lshlrev_b32_e32 v38, 16, v121
	v_and_b32_e32 v39, 0xffff0000, v121
	v_pk_add_f32 v[18:19], v[18:19], v[32:33]
	v_pk_add_f32 v[14:15], v[14:15], v[34:35]
	v_pk_add_f32 v[12:13], v[12:13], v[36:37]
	v_pk_add_f32 v[20:21], v[20:21], v[38:39]
	s_or_b64 exec, exec, s[58:59]
	v_cmp_lt_u32_e32 vcc, 2, v176
	s_and_b64 s[70:71], s[12:13], vcc
	s_and_saveexec_b64 s[58:59], s[70:71]
	v_lshlrev_b32_e32 v32, 16, v122
	v_and_b32_e32 v33, 0xffff0000, v122
	v_lshlrev_b32_e32 v34, 16, v123
	v_and_b32_e32 v35, 0xffff0000, v123
	v_lshlrev_b32_e32 v36, 16, v124
	v_and_b32_e32 v37, 0xffff0000, v124
	v_lshlrev_b32_e32 v38, 16, v125
	v_and_b32_e32 v39, 0xffff0000, v125
	v_pk_add_f32 v[18:19], v[18:19], v[32:33]
	v_pk_add_f32 v[14:15], v[14:15], v[34:35]
	v_pk_add_f32 v[12:13], v[12:13], v[36:37]
	v_pk_add_f32 v[20:21], v[20:21], v[38:39]
	s_or_b64 exec, exec, s[58:59]
	v_cmp_lt_u32_e32 vcc, 3, v176
	s_and_b64 s[70:71], s[14:15], vcc
	s_and_saveexec_b64 s[58:59], s[70:71]
	v_lshlrev_b32_e32 v32, 16, v126
	v_and_b32_e32 v33, 0xffff0000, v126
	v_lshlrev_b32_e32 v34, 16, v127
	v_and_b32_e32 v35, 0xffff0000, v127
	v_lshlrev_b32_e32 v36, 16, v128
; __global__ void __launch_bounds__(512, 2) hybrid_fwd(Args args) {
;     ...
;                 for (int j = 0; j < 16; ++j) {
;                     if (j < w && tl - j >= 0) {
;                         const u32x4 v = *(const u32x4*)(xp - (size_t)j * 512);
;                         if (j == 0) x0 = v;
; #pragma unroll
;                         for (int e = 0; e < 4; ++e) { sum[2 * e] += __builtin_bit_cast(float, v[e] << 16); sum[2 * e + 1] += __builtin_bit_cast(float, v[e] & 0xffff0000u); }
;                     }
;                 }
	v_and_b32_e32 v37, 0xffff0000, v128
	v_lshlrev_b32_e32 v38, 16, v129
	v_and_b32_e32 v39, 0xffff0000, v129
	v_pk_add_f32 v[18:19], v[18:19], v[32:33]
	v_pk_add_f32 v[14:15], v[14:15], v[34:35]
	v_pk_add_f32 v[12:13], v[12:13], v[36:37]
	v_pk_add_f32 v[20:21], v[20:21], v[38:39]
	s_or_b64 exec, exec, s[58:59]
	v_cmp_lt_u32_e32 vcc, 4, v176
	s_and_b64 s[70:71], s[16:17], vcc
	s_and_saveexec_b64 s[58:59], s[70:71]
	v_lshlrev_b32_e32 v32, 16, v130
	v_and_b32_e32 v33, 0xffff0000, v130
	v_lshlrev_b32_e32 v34, 16, v131
	v_and_b32_e32 v35, 0xffff0000, v131
	v_lshlrev_b32_e32 v36, 16, v132
	v_and_b32_e32 v37, 0xffff0000, v132
	v_lshlrev_b32_e32 v38, 16, v133
	v_and_b32_e32 v39, 0xffff0000, v133
	v_pk_add_f32 v[18:19], v[18:19], v[32:33]
	v_pk_add_f32 v[14:15], v[14:15], v[34:35]
	v_pk_add_f32 v[12:13], v[12:13], v[36:37]
	v_pk_add_f32 v[20:21], v[20:21], v[38:39]
	s_or_b64 exec, exec, s[58:59]
	v_cmp_lt_u32_e32 vcc, 5, v176
	s_and_b64 s[70:71], s[18:19], vcc
	s_and_saveexec_b64 s[58:59], s[70:71]
	v_lshlrev_b32_e32 v32, 16, v134
	v_and_b32_e32 v33, 0xffff0000, v134
	v_lshlrev_b32_e32 v34, 16, v135
	v_and_b32_e32 v35, 0xffff0000, v135
	v_lshlrev_b32_e32 v36, 16, v136
	v_and_b32_e32 v37, 0xffff0000, v136
	v_lshlrev_b32_e32 v38, 16, v137
	v_and_b32_e32 v39, 0xffff0000, v137
	v_pk_add_f32 v[18:19], v[18:19], v[32:33]
	v_pk_add_f32 v[14:15], v[14:15], v[34:35]
	v_pk_add_f32 v[12:13], v[12:13], v[36:37]
	v_pk_add_f32 v[20:21], v[20:21], v[38:39]
	s_or_b64 exec, exec, s[58:59]
	v_cmp_lt_u32_e32 vcc, 6, v176
	s_and_b64 s[70:71], s[20:21], vcc
	s_and_saveexec_b64 s[58:59], s[70:71]
	v_lshlrev_b32_e32 v32, 16, v138
	v_and_b32_e32 v33, 0xffff0000, v138
	v_lshlrev_b32_e32 v34, 16, v139
	v_and_b32_e32 v35, 0xffff0000, v139
	v_lshlrev_b32_e32 v36, 16, v140
	v_and_b32_e32 v37, 0xffff0000, v140
	v_lshlrev_b32_e32 v38, 16, v141
	v_and_b32_e32 v39, 0xffff0000, v141
	v_pk_add_f32 v[18:19], v[18:19], v[32:33]
	v_pk_add_f32 v[14:15], v[14:15], v[34:35]
	v_pk_add_f32 v[12:13], v[12:13], v[36:37]
	v_pk_add_f32 v[20:21], v[20:21], v[38:39]
	s_or_b64 exec, exec, s[58:59]
	v_cmp_lt_u32_e32 vcc, 7, v176
	s_and_b64 s[70:71], s[22:23], vcc
	s_and_saveexec_b64 s[58:59], s[70:71]
	v_lshlrev_b32_e32 v32, 16, v142
	v_and_b32_e32 v33, 0xffff0000, v142
	v_lshlrev_b32_e32 v34, 16, v143
	v_and_b32_e32 v35, 0xffff0000, v143
	v_lshlrev_b32_e32 v36, 16, v144
	v_and_b32_e32 v37, 0xffff0000, v144
	v_lshlrev_b32_e32 v38, 16, v145
	v_and_b32_e32 v39, 0xffff0000, v145
	v_pk_add_f32 v[18:19], v[18:19], v[32:33]
	v_pk_add_f32 v[14:15], v[14:15], v[34:35]
	v_pk_add_f32 v[12:13], v[12:13], v[36:37]
	v_pk_add_f32 v[20:21], v[20:21], v[38:39]
	s_or_b64 exec, exec, s[58:59]
	v_cmp_lt_u32_e32 vcc, 8, v176
	s_and_b64 s[70:71], s[24:25], vcc
	s_and_saveexec_b64 s[58:59], s[70:71]
	v_lshlrev_b32_e32 v32, 16, v146
	v_and_b32_e32 v33, 0xffff0000, v146
	v_lshlrev_b32_e32 v34, 16, v147
	v_and_b32_e32 v35, 0xffff0000, v147
	v_lshlrev_b32_e32 v36, 16, v148
	v_and_b32_e32 v37, 0xffff0000, v148
	v_lshlrev_b32_e32 v38, 16, v149
	v_and_b32_e32 v39, 0xffff0000, v149
	v_pk_add_f32 v[18:19], v[18:19], v[32:33]
	v_pk_add_f32 v[14:15], v[14:15], v[34:35]
	v_pk_add_f32 v[12:13], v[12:13], v[36:37]
	v_pk_add_f32 v[20:21], v[20:21], v[38:39]
	s_or_b64 exec, exec, s[58:59]
	v_cmp_lt_u32_e32 vcc, 9, v176
	s_and_b64 s[70:71], s[26:27], vcc
	s_and_saveexec_b64 s[58:59], s[70:71]
	v_lshlrev_b32_e32 v32, 16, v150
	v_and_b32_e32 v33, 0xffff0000, v150
	v_lshlrev_b32_e32 v34, 16, v151
	v_and_b32_e32 v35, 0xffff0000, v151
	v_lshlrev_b32_e32 v36, 16, v152
	v_and_b32_e32 v37, 0xffff0000, v152
	v_lshlrev_b32_e32 v38, 16, v153
	v_and_b32_e32 v39, 0xffff0000, v153
	v_pk_add_f32 v[18:19], v[18:19], v[32:33]
	v_pk_add_f32 v[14:15], v[14:15], v[34:35]
	v_pk_add_f32 v[12:13], v[12:13], v[36:37]
	v_pk_add_f32 v[20:21], v[20:21], v[38:39]
	s_or_b64 exec, exec, s[58:59]
	v_cmp_lt_u32_e32 vcc, 10, v176
	s_and_b64 s[70:71], s[28:29], vcc
	s_and_saveexec_b64 s[58:59], s[70:71]
	v_lshlrev_b32_e32 v32, 16, v154
	v_and_b32_e32 v33, 0xffff0000, v154
	v_lshlrev_b32_e32 v34, 16, v155
	v_and_b32_e32 v35, 0xffff0000, v155
	v_lshlrev_b32_e32 v36, 16, v156
	v_and_b32_e32 v37, 0xffff0000, v156
; __device__ __forceinline__ unsigned cvt_pk_bf16(float lo, float hi) { f32x2_t v = {lo, hi}; bf16x2_t b = __builtin_convertvector(v, bf16x2_t); return __builtin_bit_cast(unsigned, b); }
; __global__ void __launch_bounds__(512, 2) hybrid_fwd(Args args) {
;     ...
;                 for (int j = 0; j < 16; ++j) {
;                     if (j < w && tl - j >= 0) {
;                         const u32x4 v = *(const u32x4*)(xp - (size_t)j * 512);
;                         if (j == 0) x0 = v;
; #pragma unroll
;                         for (int e = 0; e < 4; ++e) { sum[2 * e] += __builtin_bit_cast(float, v[e] << 16); sum[2 * e + 1] += __builtin_bit_cast(float, v[e] & 0xffff0000u); }
;                     }
;                 }
;                 const float inv = 1.0f / (float)(tl + 1 < w ? tl + 1 : w);
;                 float p[8];
; #pragma unroll
;                 for (int e = 0; e < 4; ++e) { p[2 * e] = sum[2 * e] * inv - __builtin_bit_cast(float, x0[e] << 16); p[2 * e + 1] = sum[2 * e + 1] * inv - __builtin_bit_cast(float, x0[e] & 0xffff0000u); }
;                 u32x4 o; o.x = cvt_pk_bf16(p[0], p[1]); o.y = cvt_pk_bf16(p[2], p[3]); o.z = cvt_pk_bf16(p[4], p[5]); o.w = cvt_pk_bf16(p[6], p[7]);
;                 *(u32x4*)(POOLED + (size_t)t * 512 + cg8 * 8) = o;
;             }
	v_lshlrev_b32_e32 v38, 16, v157
	v_and_b32_e32 v39, 0xffff0000, v157
	v_pk_add_f32 v[18:19], v[18:19], v[32:33]
	v_pk_add_f32 v[14:15], v[14:15], v[34:35]
	v_pk_add_f32 v[12:13], v[12:13], v[36:37]
	v_pk_add_f32 v[20:21], v[20:21], v[38:39]
	s_or_b64 exec, exec, s[58:59]
	v_cmp_lt_u32_e32 vcc, 11, v176
	s_and_b64 s[70:71], s[30:31], vcc
	s_and_saveexec_b64 s[58:59], s[70:71]
	v_lshlrev_b32_e32 v32, 16, v158
	v_and_b32_e32 v33, 0xffff0000, v158
	v_lshlrev_b32_e32 v34, 16, v159
	v_and_b32_e32 v35, 0xffff0000, v159
	v_lshlrev_b32_e32 v36, 16, v160
	v_and_b32_e32 v37, 0xffff0000, v160
	v_lshlrev_b32_e32 v38, 16, v161
	v_and_b32_e32 v39, 0xffff0000, v161
	v_pk_add_f32 v[18:19], v[18:19], v[32:33]
	v_pk_add_f32 v[14:15], v[14:15], v[34:35]
	v_pk_add_f32 v[12:13], v[12:13], v[36:37]
	v_pk_add_f32 v[20:21], v[20:21], v[38:39]
	s_or_b64 exec, exec, s[58:59]
	v_cmp_lt_u32_e32 vcc, 12, v176
	s_and_b64 s[70:71], s[34:35], vcc
	s_and_saveexec_b64 s[58:59], s[70:71]
	v_lshlrev_b32_e32 v32, 16, v162
	v_and_b32_e32 v33, 0xffff0000, v162
	v_lshlrev_b32_e32 v34, 16, v163
	v_and_b32_e32 v35, 0xffff0000, v163
	v_lshlrev_b32_e32 v36, 16, v164
	v_and_b32_e32 v37, 0xffff0000, v164
	v_lshlrev_b32_e32 v38, 16, v165
	v_and_b32_e32 v39, 0xffff0000, v165
	v_pk_add_f32 v[18:19], v[18:19], v[32:33]
	v_pk_add_f32 v[14:15], v[14:15], v[34:35]
	v_pk_add_f32 v[12:13], v[12:13], v[36:37]
	v_pk_add_f32 v[20:21], v[20:21], v[38:39]
	s_or_b64 exec, exec, s[58:59]
	v_cmp_lt_u32_e32 vcc, 13, v176
	s_and_b64 s[70:71], s[36:37], vcc
	s_and_saveexec_b64 s[58:59], s[70:71]
	v_lshlrev_b32_e32 v32, 16, v166
	v_and_b32_e32 v33, 0xffff0000, v166
	v_lshlrev_b32_e32 v34, 16, v167
	v_and_b32_e32 v35, 0xffff0000, v167
	v_lshlrev_b32_e32 v36, 16, v168
	v_and_b32_e32 v37, 0xffff0000, v168
	v_lshlrev_b32_e32 v38, 16, v169
	v_and_b32_e32 v39, 0xffff0000, v169
	v_pk_add_f32 v[18:19], v[18:19], v[32:33]
	v_pk_add_f32 v[14:15], v[14:15], v[34:35]
	v_pk_add_f32 v[12:13], v[12:13], v[36:37]
	v_pk_add_f32 v[20:21], v[20:21], v[38:39]
	s_or_b64 exec, exec, s[58:59]
	v_cmp_lt_u32_e32 vcc, 14, v176
	s_and_b64 s[70:71], s[38:39], vcc
	s_and_saveexec_b64 s[58:59], s[70:71]
	v_lshlrev_b32_e32 v32, 16, v170
	v_and_b32_e32 v33, 0xffff0000, v170
	v_lshlrev_b32_e32 v34, 16, v171
	v_and_b32_e32 v35, 0xffff0000, v171
	v_lshlrev_b32_e32 v36, 16, v172
	v_and_b32_e32 v37, 0xffff0000, v172
	v_lshlrev_b32_e32 v38, 16, v173
	v_and_b32_e32 v39, 0xffff0000, v173
	v_pk_add_f32 v[18:19], v[18:19], v[32:33]
	v_pk_add_f32 v[14:15], v[14:15], v[34:35]
	v_pk_add_f32 v[12:13], v[12:13], v[36:37]
	v_pk_add_f32 v[20:21], v[20:21], v[38:39]
	s_or_b64 exec, exec, s[58:59]
	v_add_u32_e32 v22, 1, v176
	v_min_i32_e32 v22, v22, v28
	v_cvt_f32_i32_e32 v23, v22
	v_lshlrev_b32_e32 v22, 16, v110
	v_lshlrev_b64 v[174:175], 9, v[174:175]
	v_div_scale_f32 v24, s[58:59], v23, v23, 1.0
	v_rcp_f32_e32 v25, v24
	v_div_scale_f32 v176, vcc, 1.0, v23, 1.0
	v_fma_f32 v31, -v24, v25, 1.0
	v_fmac_f32_e32 v25, v31, v25
	v_mul_f32_e32 v31, v176, v25
	v_fma_f32 v32, -v24, v31, v176
	v_fmac_f32_e32 v31, v32, v25
	v_fma_f32 v24, -v24, v31, v176
	v_div_fmas_f32 v24, v24, v25, v31
	v_div_fixup_f32 v24, v24, v23, 1.0
	v_and_b32_e32 v23, 0xffff0000, v110
	v_lshlrev_b32_e32 v110, 16, v111
	v_and_b32_e32 v111, 0xffff0000, v111
	v_pk_fma_f32 v[14:15], v[24:25], v[14:15], v[110:111] op_sel_hi:[0,1,1] neg_lo:[0,0,1] neg_hi:[0,0,1]
	v_lshlrev_b32_e32 v110, 16, v112
	v_and_b32_e32 v111, 0xffff0000, v112
	v_pk_fma_f32 v[12:13], v[24:25], v[12:13], v[110:111] op_sel_hi:[0,1,1] neg_lo:[0,0,1] neg_hi:[0,0,1]
	v_lshlrev_b32_e32 v110, 16, v113
	v_and_b32_e32 v111, 0xffff0000, v113
	v_pk_fma_f32 v[18:19], v[24:25], v[18:19], v[22:23] op_sel_hi:[0,1,1] neg_lo:[0,0,1] neg_hi:[0,0,1]
	v_pk_fma_f32 v[20:21], v[24:25], v[20:21], v[110:111] op_sel_hi:[0,1,1] neg_lo:[0,0,1] neg_hi:[0,0,1]
	v_cvt_pk_bf16_f32 v110, v18, v19
	v_cvt_pk_bf16_f32 v111, v14, v15
	v_cvt_pk_bf16_f32 v112, v12, v13
	v_cvt_pk_bf16_f32 v113, v20, v21
	v_lshl_add_u64 v[12:13], v[174:175], 1, v[10:11]
	global_store_dwordx4 v[12:13], v[110:113], off
	v_add_u32_e32 v29, 0x400, v29
	s_add_i32 s86, s86, 1
	s_cmp_lt_u32 s86, 8
	s_cbranch_scc1 .Lp3_loop
	s_branch .LBB0_359
